# speedup vs baseline: 1.0057x; 1.0057x over previous
;   __device__ __forceinline__ const float* in(int i) const { return reinterpret_cast<const float*>(ld64(i * 8)); }
;   __device__ __forceinline__ unsigned char* ws() const { return reinterpret_cast<unsigned char*>(ld64(27 * 8)); }
; __device__ __forceinline__ void phase_convert(const PRef& p) {
;   unsigned char* ws = p.ws();
;   constexpr int U0 = 704, U1 = U0 + 352, U2 = U1 + 704, U3 = U2 + 352, U4 = U3 + 384, U5 = U4 + 128;
;   for (int u = blockIdx.x; u < U5; u += gridDim.x) {
;     if (u < U0)      convert_weight(p.in(7), p.in(8), true, 1024, DFF, 5632, (bf16*)(ws + WS_W1A), u);
.LBB0_1143:
	s_or_b64 exec, exec, s[0:1]
	s_movk_i32 s101, 0x2c0
	s_mov_b64 s[0:1], src_shared_base
	v_readlane_b32 s0, v254, 5
	s_cmp_lg_u32 s0, -1
	s_cselect_b32 s0, s0, 0
	v_mov_b32_e32 v2, s0
	v_readlane_b32 s0, v254, 6
	s_cselect_b32 s4, s1, 0
	s_cmp_lg_u32 s0, -1
	v_mov_b32_e32 v3, s4
	s_cselect_b32 s0, s0, 0
	s_cselect_b32 s1, s1, 0
	flat_load_dword v0, v[2:3] sc0 sc1
	s_waitcnt vmcnt(0)
	v_mov_b32_e32 v2, s0
	v_mov_b32_e32 v3, s1
	flat_load_dword v2, v[2:3] sc0 sc1
	s_waitcnt vmcnt(0)
	v_readlane_b32 s0, v254, 19
	v_readlane_b32 s1, v254, 20
	s_andn2_b64 vcc, exec, s[0:1]
	s_waitcnt lgkmcnt(0)
	v_readfirstlane_b32 s4, v0
	v_readfirstlane_b32 s5, v2
	s_cbranch_vccnz .LBB0_1166
	v_readlane_b32 s100, v254, 1
	v_readlane_b32 s18, v254, 0
	s_addk_i32 s18, 0xc0
	s_cmp_ge_u32 s18, s100
	s_cselect_b32 s16, s100, 0
	s_sub_i32 s18, s18, s16
	s_lshl_b32 s17, s18, 8
	s_or_b32 s17, s17, 15
	s_lshl_b32 s16, s18, 3
	s_add_i32 s16, s16, 0x7be00
